# staging waves trimmed: log2e folded into the running-sum fma, a-term as one fma with precomputed 1-k_a, plain-kk row written by the first staging wave only
# speedup vs baseline: 1.0146x; 1.0032x over previous
.Lsc_G:
	v_add_u32_e32 v1, 0xffffff00, v173
	v_lshrrev_b32_e32 v2, 3, v1
	v_and_b32_e32 v3, 7, v1
	s_and_b32 s8, s4, 7
	s_bfe_u32 s10, s4, 0x20003
	s_lshr_b32 s11, s4, 7
	s_bfe_u32 s9, s4, 0x20005
	s_lshl_b32 s9, s9, 13
	v_readlane_b32 s50, v242, 0
	v_readlane_b32 s51, v242, 1
	v_readlane_b32 s16, v242, 62
	s_load_dwordx4 s[12:15], s[50:51], 0x68
	s_add_u32 s36, s90, 0x5e00000
	s_addc_u32 s37, s91, 0
	s_add_u32 s38, s90, 0x7e00000
	s_addc_u32 s39, s91, 0
	s_add_u32 s44, s90, 0x9e00000
	s_addc_u32 s45, s91, 0
	s_add_u32 s46, s90, 0x1c00000
	s_addc_u32 s47, s91, 0
	s_lshl_b32 s68, s11, 25
	s_add_u32 s69, s68, 0x13e00000
	s_add_u32 s40, s90, s69
	s_addc_u32 s41, s91, 0
	s_add_u32 s69, s68, 0x17e00000
	s_add_u32 s42, s90, s69
	s_addc_u32 s43, s91, 0
	s_lshl_b32 s68, s11, 26
	s_add_u32 s68, s68, 0xbe00000
	s_add_u32 s48, s90, s68
	s_addc_u32 s49, s91, 0
	s_cmp_eq_u32 s11, 0
	s_mov_b32 s54, 0x8000
	s_movk_i32 s55, 0x400
	s_mov_b32 s64, 0x10000
	s_cselect_b32 s54, s54, 0xffff8000
	s_cselect_b32 s55, s55, 0xfffffc00
	s_cselect_b32 s64, s64, 0xffff0000
	s_cselect_b64 vcc, -1, 0
	v_sub_u32_e32 v4, 0x1fff, v2
	s_nop 3
	v_cndmask_b32_e32 v4, v4, v2, vcc
	v_add_u32_e32 v4, s9, v4
	s_lshl_b32 s68, s8, 7
	v_lshlrev_b32_e32 v5, 10, v4
	v_lshl_add_u32 v5, v3, 3, v5
	v_add_u32_e32 v5, s68, v5
	s_lshl_b32 s69, s8, 2
	v_lshlrev_b32_e32 v6, 5, v4
	v_add_u32_e32 v6, s69, v6
	s_lshl_b32 s69, s10, 5
	s_add_i32 s69, s69, s68
	v_lshlrev_b32_e32 v9, 10, v4
	v_lshl_add_u32 v9, v3, 2, v9
	v_add_u32_e32 v9, s69, v9
	s_lshl_b32 s65, s69, 1
	v_mul_u32_u24_e32 v8, 1024, v2
	v_lshl_add_u32 v8, v3, 4, v8
	v_add_u32_e32 v138, 512, v8
	v_add_u32_e32 v140, 35328, v8
	v_add_u32_e32 v152, -4, v0
	v_mul_u32_u24_e32 v152, 4608, v152
	v_add_u32_e32 v152, 143936, v152
	v_and_b32_e32 v156, 7, v2
	v_lshlrev_b32_e32 v153, 8, v156
	v_lshl_add_u32 v153, v3, 4, v153
	v_add_u32_e32 v153, v152, v153
	v_and_b32_e32 v154, 63, v1
	v_lshl_add_u32 v154, v154, 2, v152
	v_add_u32_e32 v155, 2048, v154
	v_add_u32_e32 v139, -1, v2
	v_mul_u32_u24_e32 v139, 1024, v139
	v_lshl_add_u32 v139, v3, 4, v139
	v_add_u32_e32 v141, 35328, v139
	v_add_u32_e32 v139, 512, v139
	v_cmp_eq_u32_e32 vcc, 0, v2
	s_nop 1
	v_cndmask_b32_e32 v139, v139, v152, vcc
	v_cndmask_b32_e32 v141, v141, v152, vcc
	v_lshrrev_b32_e32 v158, 3, v2
	v_lshlrev_b32_e32 v158, 8, v158
	v_lshl_add_u32 v158, v3, 4, v158
	v_and_b32_e32 v159, 63, v1
	v_lshlrev_b32_e32 v159, 2, v159
	v_add_u32_e32 v106, -4, v0
	v_lshl_add_u32 v159, v106, 8, v159
	v_add_u32_e32 v159, 33792, v159
	v_add_u32_e32 v106, -4, v0
	v_lshlrev_b32_e32 v162, 2, v106
	v_add_u32_e32 v162, 139808, v162
	v_mov_b32_e32 v163, 139808
	v_and_b32_e32 v181, 63, v1
	v_lshlrev_b32_e32 v181, 2, v181
	v_add_u32_e32 v181, 139840, v181
	v_lshl_add_u32 v180, v106, 8, v181
	v_cmp_gt_u32_e32 vcc, v106, v169
	s_nop 1
	v_cndmask_b32_e64 v174, 0, -1, vcc
	v_mov_b32_e32 v177, 0x7fffffff
	v_cndmask_b32_e32 v177, v177, v169, vcc
	v_cmp_lt_u32_e32 vcc, 1, v106
	s_nop 1
	v_cndmask_b32_e64 v175, 0, -1, vcc
	v_mov_b32_e32 v178, 0x7fffffff
	v_cndmask_b32_e32 v178, v178, v169, vcc
	v_cmp_lt_u32_e32 vcc, 2, v106
	s_nop 1
	v_cndmask_b32_e64 v176, 0, -1, vcc
	v_mov_b32_e32 v179, 0x7fffffff
	v_cndmask_b32_e32 v179, v179, v169, vcc
	v_add_u32_e32 v158, 32768, v158
	v_mul_u32_u24_e32 v142, 288, v3
	v_lshl_add_u32 v142, v2, 2, v142
	v_add_u32_e32 v143, 71936, v142
	v_add_u32_e32 v142, 69632, v142
	s_lshl_b32 s69, s8, 6
	s_add_i32 s69, s69, s16
	v_lshl_add_u32 v106, v3, 2, s69
	v_lshlrev_b32_e32 v106, 2, v106
	s_waitcnt lgkmcnt(0)
	global_load_dwordx4 v[12:15], v106, s[12:13]
	global_load_dwordx4 v[16:19], v106, s[12:13] offset:128
	global_load_dwordx4 v[20:23], v106, s[14:15]
	global_load_dwordx4 v[24:27], v106, s[14:15] offset:128
	global_load_dwordx2 v[28:29], v5, s[36:37]
	global_load_dwordx2 v[30:31], v5, s[36:37] offset:64
	global_load_dwordx2 v[32:33], v5, s[38:39]
	global_load_dwordx2 v[34:35], v5, s[38:39] offset:64
	global_load_dwordx2 v[36:37], v5, s[40:41]
	global_load_dwordx2 v[38:39], v5, s[40:41] offset:64
	global_load_dwordx2 v[40:41], v5, s[42:43]
	global_load_dwordx2 v[42:43], v5, s[42:43] offset:64
	global_load_dword v44, v6, s[46:47]
	global_load_dword v45, v9, s[44:45]
	v_add_u32_e32 v5, s54, v5
	v_add_u32_e32 v6, s55, v6
	v_add_u32_e32 v9, s54, v9
	global_load_dwordx2 v[46:47], v5, s[36:37]
	global_load_dwordx2 v[48:49], v5, s[36:37] offset:64
	global_load_dwordx2 v[50:51], v5, s[38:39]
	global_load_dwordx2 v[52:53], v5, s[38:39] offset:64
	global_load_dwordx2 v[54:55], v5, s[40:41]
	global_load_dwordx2 v[56:57], v5, s[40:41] offset:64
	global_load_dwordx2 v[58:59], v5, s[42:43]
	global_load_dwordx2 v[60:61], v5, s[42:43] offset:64
	global_load_dword v62, v6, s[46:47]
	global_load_dword v63, v9, s[44:45]
	v_add_u32_e32 v5, s54, v5
	v_add_u32_e32 v6, s55, v6
	v_add_u32_e32 v9, s54, v9
	v_and_b32_e32 v166, 15, v1
	v_lshrrev_b32_e32 v167, 4, v1
	v_sub_u32_e32 v4, 0x1fff, v167
	s_cmp_eq_u32 s11, 0
	s_cselect_b64 vcc, -1, 0
	s_nop 3
	v_cndmask_b32_e32 v4, v4, v167, vcc
	v_add_u32_e32 v4, s9, v4
	v_lshlrev_b32_e32 v7, 11, v4
	v_lshl_add_u32 v7, v166, 2, v7
	v_add_u32_e32 v7, s65, v7
	s_ashr_i32 s65, s64, 1
	v_add_u32_e32 v165, s65, v7
	v_lshlrev_b32_e32 v11, 10, v167
	v_lshl_add_u32 v11, v166, 6, v11
	v_add_u32_e32 v11, 74240, v11
	v_lshrrev_b32_e32 v166, 2, v166
	v_add_u32_e32 v2, 0, v166
	v_and_b32_e32 v2, 3, v2
	v_lshl_add_u32 v2, v2, 4, v11
	v_add_u32_e32 v3, 1, v166
	v_and_b32_e32 v3, 3, v3
	v_lshl_add_u32 v3, v3, 4, v11
	v_add_u32_e32 v4, 2, v166
	v_and_b32_e32 v4, 3, v4
	v_lshl_add_u32 v4, v4, 4, v11
	v_add_u32_e32 v10, 3, v166
	v_and_b32_e32 v10, 3, v10
	v_lshl_add_u32 v10, v10, 4, v11
	s_waitcnt vmcnt(20)
	v_pk_add_f32 v[190:191], v[20:21], 1.0 op_sel_hi:[1,0] neg_lo:[1,0] neg_hi:[1,0]
	v_pk_add_f32 v[192:193], v[22:23], 1.0 op_sel_hi:[1,0] neg_lo:[1,0] neg_hi:[1,0]
	v_pk_add_f32 v[194:195], v[24:25], 1.0 op_sel_hi:[1,0] neg_lo:[1,0] neg_hi:[1,0]
	v_pk_add_f32 v[196:197], v[26:27], 1.0 op_sel_hi:[1,0] neg_lo:[1,0] neg_hi:[1,0]
	v_cmp_eq_u32_e64 s[12:13], 0, v156
	s_mov_b32 s14, 0x3fb8aa3b
	s_mov_b32 s6, 0
	v_mov_b32_e32 v144, 139792
	v_mov_b32_e32 v145, v164
	v_mov_b32_e32 v146, 0
	s_waitcnt vmcnt(10)
	v_lshlrev_b32_e32 v64, 16, v36
	v_and_b32_e32 v65, 0xffff0000, v36
	v_lshlrev_b32_e32 v66, 16, v37
	v_and_b32_e32 v67, 0xffff0000, v37
	v_lshlrev_b32_e32 v68, 16, v38
	v_and_b32_e32 v69, 0xffff0000, v38
	v_lshlrev_b32_e32 v70, 16, v39
	v_and_b32_e32 v71, 0xffff0000, v39
	ds_write_b128 v153, v[64:67]
	ds_write_b128 v153, v[68:71] offset:128
	s_waitcnt lgkmcnt(0)
	ds_read_b32 v124, v154 offset:0
	ds_read_b32 v125, v154 offset:256
	ds_read_b32 v126, v154 offset:512
	ds_read_b32 v127, v154 offset:768
	ds_read_b32 v128, v154 offset:1024
	ds_read_b32 v129, v154 offset:1280
	ds_read_b32 v130, v154 offset:1536
	ds_read_b32 v131, v154 offset:1792
	v_lshlrev_b32_e32 v108, 16, v32
	v_and_b32_e32 v109, 0xffff0000, v32
	v_lshlrev_b32_e32 v110, 16, v40
	v_and_b32_e32 v111, 0xffff0000, v40
	v_lshlrev_b32_e32 v96, 16, v28
	v_and_b32_e32 v97, 0xffff0000, v28
	v_pk_mul_f32 v[114:115], v[12:13], v[108:109]
	v_pk_fma_f32 v[112:113], v[20:21], v[110:111], v[190:191]
	v_pk_mul_f32 v[88:89], v[44:45], v[114:115] op_sel_hi:[0,1]
	v_pk_mul_f32 v[72:73], v[112:113], v[108:109]
	v_pk_mul_f32 v[80:81], v[88:89], v[110:111]
	v_lshlrev_b32_e32 v108, 16, v33
	v_and_b32_e32 v109, 0xffff0000, v33
	v_lshlrev_b32_e32 v110, 16, v41
	v_and_b32_e32 v111, 0xffff0000, v41
	v_lshlrev_b32_e32 v98, 16, v29
	v_and_b32_e32 v99, 0xffff0000, v29
	v_pk_mul_f32 v[114:115], v[14:15], v[108:109]
	v_pk_fma_f32 v[112:113], v[22:23], v[110:111], v[192:193]
	v_pk_mul_f32 v[90:91], v[44:45], v[114:115] op_sel_hi:[0,1]
	v_pk_mul_f32 v[74:75], v[112:113], v[108:109]
	v_pk_mul_f32 v[82:83], v[90:91], v[110:111]
	v_lshlrev_b32_e32 v108, 16, v34
	v_and_b32_e32 v109, 0xffff0000, v34
	v_lshlrev_b32_e32 v110, 16, v42
	v_and_b32_e32 v111, 0xffff0000, v42
	v_lshlrev_b32_e32 v100, 16, v30
	v_and_b32_e32 v101, 0xffff0000, v30
	v_pk_mul_f32 v[114:115], v[16:17], v[108:109]
	v_pk_fma_f32 v[112:113], v[24:25], v[110:111], v[194:195]
	v_pk_mul_f32 v[92:93], v[44:45], v[114:115] op_sel_hi:[0,1]
	v_pk_mul_f32 v[76:77], v[112:113], v[108:109]
	v_pk_mul_f32 v[84:85], v[92:93], v[110:111]
	v_lshlrev_b32_e32 v108, 16, v35
	v_and_b32_e32 v109, 0xffff0000, v35
	v_lshlrev_b32_e32 v110, 16, v43
	v_and_b32_e32 v111, 0xffff0000, v43
	v_lshlrev_b32_e32 v102, 16, v31
	v_and_b32_e32 v103, 0xffff0000, v31
	v_pk_mul_f32 v[114:115], v[18:19], v[108:109]
	v_pk_fma_f32 v[112:113], v[26:27], v[110:111], v[196:197]
	v_pk_mul_f32 v[94:95], v[44:45], v[114:115] op_sel_hi:[0,1]
	v_pk_mul_f32 v[78:79], v[112:113], v[108:109]
	v_pk_mul_f32 v[86:87], v[94:95], v[110:111]
	v_lshlrev_b32_e32 v104, 16, v45
	v_and_b32_e32 v105, 0xffff0000, v45
	s_waitcnt lgkmcnt(0)
	v_add_f32_e32 v125, v124, v125
	v_add_f32_e32 v126, v125, v126
	v_add_f32_e32 v127, v126, v127
	v_add_f32_e32 v128, v127, v128
	v_add_f32_e32 v129, v128, v129
	v_add_f32_e32 v130, v129, v130
	v_add_f32_e32 v131, v130, v131
	s_and_b32 s72, s6, 3
	s_lshl_b32 s72, s72, 10
	v_add_u32_e32 v182, s72, v180
	v_add_u32_e32 v183, s72, v181
	v_mul_f32_e32 v189, 0x3fb8aa3b, v131
	ds_write_b32 v182, v189
	v_add_u32_e32 v184, 1, v146
	s_waitcnt lgkmcnt(0)
	ds_write_b32 v162, v184
	s_add_u32 s73, s6, 1
	s_mov_b32 s69, 0x100000

.Lsc_gf_go1:
	ds_read_b32 v185, v183
	ds_read_b32 v186, v183 offset:256
	ds_read_b32 v187, v183 offset:512
	s_waitcnt lgkmcnt(0)
	v_and_b32_e32 v185, v174, v185
	v_and_b32_e32 v186, v175, v186
	v_and_b32_e32 v187, v176, v187
	v_add_f32_e32 v185, v185, v186
	v_add_f32_e32 v185, v185, v187
	v_fma_f32 v124, v124, s14, v185
	v_fma_f32 v125, v125, s14, v185
	v_fma_f32 v126, v126, s14, v185
	v_fma_f32 v127, v127, s14, v185
	v_fma_f32 v128, v128, s14, v185
	v_fma_f32 v129, v129, s14, v185
	v_fma_f32 v130, v130, s14, v185
	v_fma_f32 v131, v131, s14, v185
	v_exp_f32_e64 v188, -v185
	v_exp_f32_e64 v124, -v124
	v_exp_f32_e64 v125, -v125
	v_exp_f32_e64 v126, -v126
	v_exp_f32_e64 v127, -v127
	v_exp_f32_e64 v128, -v128
	v_exp_f32_e64 v129, -v129
	v_exp_f32_e64 v130, -v130
	v_exp_f32_e64 v131, -v131
	s_nop 0
	ds_write_b32 v155, v188
	ds_write_b32 v155, v124 offset:256
	ds_write_b32 v155, v125 offset:512
	ds_write_b32 v155, v126 offset:768
	ds_write_b32 v155, v127 offset:1024
	ds_write_b32 v155, v128 offset:1280
	ds_write_b32 v155, v129 offset:1536
	ds_write_b32 v155, v130 offset:1792
	ds_write_b32 v155, v131 offset:2048
	v_mov_b32_e32 v161, v131
	s_waitcnt lgkmcnt(0)
	ds_read_b128 v[64:67], v153 offset:2048
	ds_read_b128 v[68:71], v153 offset:2176
	ds_read_b128 v[116:119], v153 offset:2304
	ds_read_b128 v[120:123], v153 offset:2432
	s_waitcnt lgkmcnt(0)
	v_rcp_f32_e32 v124, v116
	v_rcp_f32_e32 v125, v117
	v_rcp_f32_e32 v126, v118
	v_rcp_f32_e32 v127, v119
	v_rcp_f32_e32 v128, v120
	v_rcp_f32_e32 v129, v121
	v_rcp_f32_e32 v130, v122
	v_rcp_f32_e32 v131, v123
	s_nop 1
	v_pk_mul_f32 v[72:73], v[72:73], v[124:125]
	v_pk_mul_f32 v[80:81], v[80:81], v[124:125]
	v_pk_mul_f32 v[88:89], v[88:89], v[64:65]
	v_pk_mul_f32 v[96:97], v[96:97], v[116:117]
	v_pk_mul_f32 v[74:75], v[74:75], v[126:127]
	v_pk_mul_f32 v[82:83], v[82:83], v[126:127]
	v_pk_mul_f32 v[90:91], v[90:91], v[66:67]
	v_pk_mul_f32 v[98:99], v[98:99], v[118:119]
	v_pk_mul_f32 v[76:77], v[76:77], v[128:129]
	v_pk_mul_f32 v[84:85], v[84:85], v[128:129]
	v_pk_mul_f32 v[92:93], v[92:93], v[68:69]
	v_pk_mul_f32 v[100:101], v[100:101], v[120:121]
	v_pk_mul_f32 v[78:79], v[78:79], v[130:131]
	v_pk_mul_f32 v[86:87], v[86:87], v[130:131]
	v_pk_mul_f32 v[94:95], v[94:95], v[70:71]
	v_pk_mul_f32 v[102:103], v[102:103], v[122:123]
	global_load_dwordx2 v[28:29], v5, s[36:37]
	global_load_dwordx2 v[30:31], v5, s[36:37] offset:64
	global_load_dwordx2 v[32:33], v5, s[38:39]
	global_load_dwordx2 v[34:35], v5, s[38:39] offset:64
	global_load_dwordx2 v[36:37], v5, s[40:41]
	global_load_dwordx2 v[38:39], v5, s[40:41] offset:64
	global_load_dwordx2 v[40:41], v5, s[42:43]
	global_load_dwordx2 v[42:43], v5, s[42:43] offset:64
	global_load_dword v44, v6, s[46:47]
	global_load_dword v45, v9, s[44:45]
	v_add_u32_e32 v5, s54, v5
	v_add_u32_e32 v6, s55, v6
	v_add_u32_e32 v9, s54, v9
	ds_write_b32 v159, v161 offset:0
	ds_write_b128 v8, v[72:75] offset:0
	ds_write_b128 v8, v[76:79] offset:128
	ds_write_b128 v8, v[80:83] offset:256
	ds_write_b128 v8, v[84:87] offset:384
	ds_write2_b32 v138, v96, v97 offset0:1 offset1:3
	ds_write2_b32 v139, v88, v89 offset0:0 offset1:2
	ds_write2_b32 v138, v98, v99 offset0:65 offset1:67
	ds_write2_b32 v139, v90, v91 offset0:64 offset1:66
	ds_write2_b32 v138, v100, v101 offset0:33 offset1:35
	ds_write2_b32 v139, v92, v93 offset0:32 offset1:34
	ds_write2_b32 v138, v102, v103 offset0:97 offset1:99
	ds_write2_b32 v139, v94, v95 offset0:96 offset1:98
	ds_write2_b32 v142, v104, v105 offset1:36
	s_cmp_lg_u32 s7, 4
	s_cbranch_scc1 .Lsc_nokb1
	s_and_saveexec_b64 s[68:69], s[12:13]
	ds_write_b128 v158, v[88:91] offset:0
	ds_write_b128 v158, v[92:95] offset:128
	s_mov_b64 exec, s[68:69]
.Lsc_nokb1:
	s_add_i32 s6, s6, 1
	v_add_u32_e32 v146, 1, v146
	s_waitcnt lgkmcnt(0)
	ds_write_b32 v145, v146
	s_waitcnt vmcnt(10)
	v_lshlrev_b32_e32 v64, 16, v54
	v_and_b32_e32 v65, 0xffff0000, v54
	v_lshlrev_b32_e32 v66, 16, v55
	v_and_b32_e32 v67, 0xffff0000, v55
	v_lshlrev_b32_e32 v68, 16, v56
	v_and_b32_e32 v69, 0xffff0000, v56
	v_lshlrev_b32_e32 v70, 16, v57
	v_and_b32_e32 v71, 0xffff0000, v57
	ds_write_b128 v153, v[64:67]
	ds_write_b128 v153, v[68:71] offset:128
	s_waitcnt lgkmcnt(0)
	ds_read_b32 v124, v154 offset:0
	ds_read_b32 v125, v154 offset:256
	ds_read_b32 v126, v154 offset:512
	ds_read_b32 v127, v154 offset:768
	ds_read_b32 v128, v154 offset:1024
	ds_read_b32 v129, v154 offset:1280
	ds_read_b32 v130, v154 offset:1536
	ds_read_b32 v131, v154 offset:1792
	v_lshlrev_b32_e32 v108, 16, v50
	v_and_b32_e32 v109, 0xffff0000, v50
	v_lshlrev_b32_e32 v110, 16, v58
	v_and_b32_e32 v111, 0xffff0000, v58
	v_lshlrev_b32_e32 v96, 16, v46
	v_and_b32_e32 v97, 0xffff0000, v46
	v_pk_mul_f32 v[114:115], v[12:13], v[108:109]
	v_pk_fma_f32 v[112:113], v[20:21], v[110:111], v[190:191]
	v_pk_mul_f32 v[88:89], v[62:63], v[114:115] op_sel_hi:[0,1]
	v_pk_mul_f32 v[72:73], v[112:113], v[108:109]
	v_pk_mul_f32 v[80:81], v[88:89], v[110:111]
	v_lshlrev_b32_e32 v108, 16, v51
	v_and_b32_e32 v109, 0xffff0000, v51
	v_lshlrev_b32_e32 v110, 16, v59
	v_and_b32_e32 v111, 0xffff0000, v59
	v_lshlrev_b32_e32 v98, 16, v47
	v_and_b32_e32 v99, 0xffff0000, v47
	v_pk_mul_f32 v[114:115], v[14:15], v[108:109]
	v_pk_fma_f32 v[112:113], v[22:23], v[110:111], v[192:193]
	v_pk_mul_f32 v[90:91], v[62:63], v[114:115] op_sel_hi:[0,1]
	v_pk_mul_f32 v[74:75], v[112:113], v[108:109]
	v_pk_mul_f32 v[82:83], v[90:91], v[110:111]
	v_lshlrev_b32_e32 v108, 16, v52
	v_and_b32_e32 v109, 0xffff0000, v52
	v_lshlrev_b32_e32 v110, 16, v60
	v_and_b32_e32 v111, 0xffff0000, v60
	v_lshlrev_b32_e32 v100, 16, v48
	v_and_b32_e32 v101, 0xffff0000, v48
	v_pk_mul_f32 v[114:115], v[16:17], v[108:109]
	v_pk_fma_f32 v[112:113], v[24:25], v[110:111], v[194:195]
	v_pk_mul_f32 v[92:93], v[62:63], v[114:115] op_sel_hi:[0,1]
	v_pk_mul_f32 v[76:77], v[112:113], v[108:109]
	v_pk_mul_f32 v[84:85], v[92:93], v[110:111]
	v_lshlrev_b32_e32 v108, 16, v53
	v_and_b32_e32 v109, 0xffff0000, v53
	v_lshlrev_b32_e32 v110, 16, v61
	v_and_b32_e32 v111, 0xffff0000, v61
	v_lshlrev_b32_e32 v102, 16, v49
	v_and_b32_e32 v103, 0xffff0000, v49
	v_pk_mul_f32 v[114:115], v[18:19], v[108:109]
	v_pk_fma_f32 v[112:113], v[26:27], v[110:111], v[196:197]
	v_pk_mul_f32 v[94:95], v[62:63], v[114:115] op_sel_hi:[0,1]
	v_pk_mul_f32 v[78:79], v[112:113], v[108:109]
	v_pk_mul_f32 v[86:87], v[94:95], v[110:111]
	v_lshlrev_b32_e32 v104, 16, v63
	v_and_b32_e32 v105, 0xffff0000, v63
	s_waitcnt lgkmcnt(0)
	v_add_f32_e32 v125, v124, v125
	v_add_f32_e32 v126, v125, v126
	v_add_f32_e32 v127, v126, v127
	v_add_f32_e32 v128, v127, v128
	v_add_f32_e32 v129, v128, v129
	v_add_f32_e32 v130, v129, v130
	v_add_f32_e32 v131, v130, v131
	s_and_b32 s72, s6, 3
	s_lshl_b32 s72, s72, 10
	v_add_u32_e32 v182, s72, v180
	v_add_u32_e32 v183, s72, v181
	v_mul_f32_e32 v189, 0x3fb8aa3b, v131
	ds_write_b32 v182, v189
	v_add_u32_e32 v184, 1, v146
	s_waitcnt lgkmcnt(0)
	ds_write_b32 v162, v184
	s_add_u32 s73, s6, 1
	s_mov_b32 s69, 0x100000

.Lsc_gf_go2:
	ds_read_b32 v185, v183
	ds_read_b32 v186, v183 offset:256
	ds_read_b32 v187, v183 offset:512
	s_waitcnt lgkmcnt(0)
	v_and_b32_e32 v185, v174, v185
	v_and_b32_e32 v186, v175, v186
	v_and_b32_e32 v187, v176, v187
	v_add_f32_e32 v185, v185, v186
	v_add_f32_e32 v185, v185, v187
	v_fma_f32 v124, v124, s14, v185
	v_fma_f32 v125, v125, s14, v185
	v_fma_f32 v126, v126, s14, v185
	v_fma_f32 v127, v127, s14, v185
	v_fma_f32 v128, v128, s14, v185
	v_fma_f32 v129, v129, s14, v185
	v_fma_f32 v130, v130, s14, v185
	v_fma_f32 v131, v131, s14, v185
	v_exp_f32_e64 v188, -v185
	v_exp_f32_e64 v124, -v124
	v_exp_f32_e64 v125, -v125
	v_exp_f32_e64 v126, -v126
	v_exp_f32_e64 v127, -v127
	v_exp_f32_e64 v128, -v128
	v_exp_f32_e64 v129, -v129
	v_exp_f32_e64 v130, -v130
	v_exp_f32_e64 v131, -v131
	s_nop 0
	ds_write_b32 v155, v188
	ds_write_b32 v155, v124 offset:256
	ds_write_b32 v155, v125 offset:512
	ds_write_b32 v155, v126 offset:768
	ds_write_b32 v155, v127 offset:1024
	ds_write_b32 v155, v128 offset:1280
	ds_write_b32 v155, v129 offset:1536
	ds_write_b32 v155, v130 offset:1792
	ds_write_b32 v155, v131 offset:2048
	v_mov_b32_e32 v161, v131
	s_waitcnt lgkmcnt(0)
	ds_read_b128 v[64:67], v153 offset:2048
	ds_read_b128 v[68:71], v153 offset:2176
	ds_read_b128 v[116:119], v153 offset:2304
	ds_read_b128 v[120:123], v153 offset:2432
	s_waitcnt lgkmcnt(0)
	v_rcp_f32_e32 v124, v116
	v_rcp_f32_e32 v125, v117
	v_rcp_f32_e32 v126, v118
	v_rcp_f32_e32 v127, v119
	v_rcp_f32_e32 v128, v120
	v_rcp_f32_e32 v129, v121
	v_rcp_f32_e32 v130, v122
	v_rcp_f32_e32 v131, v123
	s_nop 1
	v_pk_mul_f32 v[72:73], v[72:73], v[124:125]
	v_pk_mul_f32 v[80:81], v[80:81], v[124:125]
	v_pk_mul_f32 v[88:89], v[88:89], v[64:65]
	v_pk_mul_f32 v[96:97], v[96:97], v[116:117]
	v_pk_mul_f32 v[74:75], v[74:75], v[126:127]
	v_pk_mul_f32 v[82:83], v[82:83], v[126:127]
	v_pk_mul_f32 v[90:91], v[90:91], v[66:67]
	v_pk_mul_f32 v[98:99], v[98:99], v[118:119]
	v_pk_mul_f32 v[76:77], v[76:77], v[128:129]
	v_pk_mul_f32 v[84:85], v[84:85], v[128:129]
	v_pk_mul_f32 v[92:93], v[92:93], v[68:69]
	v_pk_mul_f32 v[100:101], v[100:101], v[120:121]
	v_pk_mul_f32 v[78:79], v[78:79], v[130:131]
	v_pk_mul_f32 v[86:87], v[86:87], v[130:131]
	v_pk_mul_f32 v[94:95], v[94:95], v[70:71]
	v_pk_mul_f32 v[102:103], v[102:103], v[122:123]
	global_load_dwordx2 v[46:47], v5, s[36:37]
	global_load_dwordx2 v[48:49], v5, s[36:37] offset:64
	global_load_dwordx2 v[50:51], v5, s[38:39]
	global_load_dwordx2 v[52:53], v5, s[38:39] offset:64
	global_load_dwordx2 v[54:55], v5, s[40:41]
	global_load_dwordx2 v[56:57], v5, s[40:41] offset:64
	global_load_dwordx2 v[58:59], v5, s[42:43]
	global_load_dwordx2 v[60:61], v5, s[42:43] offset:64
	global_load_dword v62, v6, s[46:47]
	global_load_dword v63, v9, s[44:45]
	v_add_u32_e32 v5, s54, v5
	v_add_u32_e32 v6, s55, v6
	v_add_u32_e32 v9, s54, v9
	ds_write_b32 v159, v161 offset:34816
	ds_write_b128 v8, v[72:75] offset:34816
	ds_write_b128 v8, v[76:79] offset:34944
	ds_write_b128 v8, v[80:83] offset:35072
	ds_write_b128 v8, v[84:87] offset:35200
	ds_write2_b32 v140, v96, v97 offset0:1 offset1:3
	ds_write2_b32 v141, v88, v89 offset0:0 offset1:2
	ds_write2_b32 v140, v98, v99 offset0:65 offset1:67
	ds_write2_b32 v141, v90, v91 offset0:64 offset1:66
	ds_write2_b32 v140, v100, v101 offset0:33 offset1:35
	ds_write2_b32 v141, v92, v93 offset0:32 offset1:34
	ds_write2_b32 v140, v102, v103 offset0:97 offset1:99
	ds_write2_b32 v141, v94, v95 offset0:96 offset1:98
	ds_write2_b32 v143, v104, v105 offset1:36
	s_cmp_lg_u32 s7, 4
	s_cbranch_scc1 .Lsc_nokb2
	s_and_saveexec_b64 s[68:69], s[12:13]
	ds_write_b128 v158, v[88:91] offset:34816
	ds_write_b128 v158, v[92:95] offset:34944
	s_mov_b64 exec, s[68:69]
.Lsc_nokb2:
	s_add_i32 s6, s6, 1
	v_add_u32_e32 v146, 1, v146
	s_waitcnt lgkmcnt(0)
	ds_write_b32 v145, v146
.Lsc_G_loop:
	s_waitcnt vmcnt(10)
	v_lshlrev_b32_e32 v64, 16, v36
	v_and_b32_e32 v65, 0xffff0000, v36
	v_lshlrev_b32_e32 v66, 16, v37
	v_and_b32_e32 v67, 0xffff0000, v37
	v_lshlrev_b32_e32 v68, 16, v38
	v_and_b32_e32 v69, 0xffff0000, v38
	v_lshlrev_b32_e32 v70, 16, v39
	v_and_b32_e32 v71, 0xffff0000, v39
	ds_write_b128 v153, v[64:67]
	ds_write_b128 v153, v[68:71] offset:128
	s_waitcnt lgkmcnt(0)
	ds_read_b32 v124, v154 offset:0
	ds_read_b32 v125, v154 offset:256
	ds_read_b32 v126, v154 offset:512
	ds_read_b32 v127, v154 offset:768
	ds_read_b32 v128, v154 offset:1024
	ds_read_b32 v129, v154 offset:1280
	ds_read_b32 v130, v154 offset:1536
	ds_read_b32 v131, v154 offset:1792
	v_lshlrev_b32_e32 v108, 16, v32
	v_and_b32_e32 v109, 0xffff0000, v32
	v_lshlrev_b32_e32 v110, 16, v40
	v_and_b32_e32 v111, 0xffff0000, v40
	v_lshlrev_b32_e32 v96, 16, v28
	v_and_b32_e32 v97, 0xffff0000, v28
	v_pk_mul_f32 v[114:115], v[12:13], v[108:109]
	v_pk_fma_f32 v[112:113], v[20:21], v[110:111], v[190:191]
	v_pk_mul_f32 v[88:89], v[44:45], v[114:115] op_sel_hi:[0,1]
	v_pk_mul_f32 v[72:73], v[112:113], v[108:109]
	v_pk_mul_f32 v[80:81], v[88:89], v[110:111]
	v_lshlrev_b32_e32 v108, 16, v33
	v_and_b32_e32 v109, 0xffff0000, v33
	v_lshlrev_b32_e32 v110, 16, v41
	v_and_b32_e32 v111, 0xffff0000, v41
	v_lshlrev_b32_e32 v98, 16, v29
	v_and_b32_e32 v99, 0xffff0000, v29
	v_pk_mul_f32 v[114:115], v[14:15], v[108:109]
	v_pk_fma_f32 v[112:113], v[22:23], v[110:111], v[192:193]
	v_pk_mul_f32 v[90:91], v[44:45], v[114:115] op_sel_hi:[0,1]
	v_pk_mul_f32 v[74:75], v[112:113], v[108:109]
	v_pk_mul_f32 v[82:83], v[90:91], v[110:111]
	v_lshlrev_b32_e32 v108, 16, v34
	v_and_b32_e32 v109, 0xffff0000, v34
	v_lshlrev_b32_e32 v110, 16, v42
	v_and_b32_e32 v111, 0xffff0000, v42
	v_lshlrev_b32_e32 v100, 16, v30
	v_and_b32_e32 v101, 0xffff0000, v30
	v_pk_mul_f32 v[114:115], v[16:17], v[108:109]
	v_pk_fma_f32 v[112:113], v[24:25], v[110:111], v[194:195]
	v_pk_mul_f32 v[92:93], v[44:45], v[114:115] op_sel_hi:[0,1]
	v_pk_mul_f32 v[76:77], v[112:113], v[108:109]
	v_pk_mul_f32 v[84:85], v[92:93], v[110:111]
	v_lshlrev_b32_e32 v108, 16, v35
	v_and_b32_e32 v109, 0xffff0000, v35
	v_lshlrev_b32_e32 v110, 16, v43
	v_and_b32_e32 v111, 0xffff0000, v43
	v_lshlrev_b32_e32 v102, 16, v31
	v_and_b32_e32 v103, 0xffff0000, v31
	v_pk_mul_f32 v[114:115], v[18:19], v[108:109]
	v_pk_fma_f32 v[112:113], v[26:27], v[110:111], v[196:197]
	v_pk_mul_f32 v[94:95], v[44:45], v[114:115] op_sel_hi:[0,1]
	v_pk_mul_f32 v[78:79], v[112:113], v[108:109]
	v_pk_mul_f32 v[86:87], v[94:95], v[110:111]
	v_lshlrev_b32_e32 v104, 16, v45
	v_and_b32_e32 v105, 0xffff0000, v45
	s_waitcnt lgkmcnt(0)
	v_add_f32_e32 v125, v124, v125
	v_add_f32_e32 v126, v125, v126
	v_add_f32_e32 v127, v126, v127
	v_add_f32_e32 v128, v127, v128
	v_add_f32_e32 v129, v128, v129
	v_add_f32_e32 v130, v129, v130
	v_add_f32_e32 v131, v130, v131
	s_and_b32 s72, s6, 3
	s_lshl_b32 s72, s72, 10
	v_add_u32_e32 v182, s72, v180
	v_add_u32_e32 v183, s72, v181
	v_mul_f32_e32 v189, 0x3fb8aa3b, v131
	ds_write_b32 v182, v189
	v_add_u32_e32 v184, 1, v146
	s_waitcnt lgkmcnt(0)
	ds_write_b32 v162, v184
	s_add_u32 s73, s6, 1
	s_mov_b32 s69, 0x100000

.Lsc_gf_go3:
	ds_read_b32 v185, v183
	ds_read_b32 v186, v183 offset:256
	ds_read_b32 v187, v183 offset:512
	s_waitcnt lgkmcnt(0)
	v_and_b32_e32 v185, v174, v185
	v_and_b32_e32 v186, v175, v186
	v_and_b32_e32 v187, v176, v187
	v_add_f32_e32 v185, v185, v186
	v_add_f32_e32 v185, v185, v187
	v_fma_f32 v124, v124, s14, v185
	v_fma_f32 v125, v125, s14, v185
	v_fma_f32 v126, v126, s14, v185
	v_fma_f32 v127, v127, s14, v185
	v_fma_f32 v128, v128, s14, v185
	v_fma_f32 v129, v129, s14, v185
	v_fma_f32 v130, v130, s14, v185
	v_fma_f32 v131, v131, s14, v185
	v_exp_f32_e64 v188, -v185
	v_exp_f32_e64 v124, -v124
	v_exp_f32_e64 v125, -v125
	v_exp_f32_e64 v126, -v126
	v_exp_f32_e64 v127, -v127
	v_exp_f32_e64 v128, -v128
	v_exp_f32_e64 v129, -v129
	v_exp_f32_e64 v130, -v130
	v_exp_f32_e64 v131, -v131
	s_nop 0
	ds_write_b32 v155, v188
	ds_write_b32 v155, v124 offset:256
	ds_write_b32 v155, v125 offset:512
	ds_write_b32 v155, v126 offset:768
	ds_write_b32 v155, v127 offset:1024
	ds_write_b32 v155, v128 offset:1280
	ds_write_b32 v155, v129 offset:1536
	ds_write_b32 v155, v130 offset:1792
	ds_write_b32 v155, v131 offset:2048
	v_mov_b32_e32 v161, v131
	s_waitcnt lgkmcnt(0)
	ds_read_b128 v[64:67], v153 offset:2048
	ds_read_b128 v[68:71], v153 offset:2176
	ds_read_b128 v[116:119], v153 offset:2304
	ds_read_b128 v[120:123], v153 offset:2432
	s_waitcnt lgkmcnt(0)
	v_rcp_f32_e32 v124, v116
	v_rcp_f32_e32 v125, v117
	v_rcp_f32_e32 v126, v118
	v_rcp_f32_e32 v127, v119
	v_rcp_f32_e32 v128, v120
	v_rcp_f32_e32 v129, v121
	v_rcp_f32_e32 v130, v122
	v_rcp_f32_e32 v131, v123
	s_nop 1
	v_pk_mul_f32 v[72:73], v[72:73], v[124:125]
	v_pk_mul_f32 v[80:81], v[80:81], v[124:125]
	v_pk_mul_f32 v[88:89], v[88:89], v[64:65]
	v_pk_mul_f32 v[96:97], v[96:97], v[116:117]
	v_pk_mul_f32 v[74:75], v[74:75], v[126:127]
	v_pk_mul_f32 v[82:83], v[82:83], v[126:127]
	v_pk_mul_f32 v[90:91], v[90:91], v[66:67]
	v_pk_mul_f32 v[98:99], v[98:99], v[118:119]
	v_pk_mul_f32 v[76:77], v[76:77], v[128:129]
	v_pk_mul_f32 v[84:85], v[84:85], v[128:129]
	v_pk_mul_f32 v[92:93], v[92:93], v[68:69]
	v_pk_mul_f32 v[100:101], v[100:101], v[120:121]
	v_pk_mul_f32 v[78:79], v[78:79], v[130:131]
	v_pk_mul_f32 v[86:87], v[86:87], v[130:131]
	v_pk_mul_f32 v[94:95], v[94:95], v[70:71]
	v_pk_mul_f32 v[102:103], v[102:103], v[122:123]
	global_load_dwordx2 v[28:29], v5, s[36:37]
	global_load_dwordx2 v[30:31], v5, s[36:37] offset:64
	global_load_dwordx2 v[32:33], v5, s[38:39]
	global_load_dwordx2 v[34:35], v5, s[38:39] offset:64
	global_load_dwordx2 v[36:37], v5, s[40:41]
	global_load_dwordx2 v[38:39], v5, s[40:41] offset:64
	global_load_dwordx2 v[40:41], v5, s[42:43]
	global_load_dwordx2 v[42:43], v5, s[42:43] offset:64
	global_load_dword v44, v6, s[46:47]
	global_load_dword v45, v9, s[44:45]
	v_add_u32_e32 v5, s54, v5
	v_add_u32_e32 v6, s55, v6
	v_add_u32_e32 v9, s54, v9
	s_sub_u32 s65, s6, 1
	ds_read_b128 v[148:151], v144
	s_waitcnt lgkmcnt(0)
	v_min_u32_e32 v148, v148, v149
	v_min3_u32 v148, v148, v150, v151
	s_nop 1
	v_readfirstlane_b32 s68, v148
	s_cmp_ge_u32 s68, s65
	s_cbranch_scc1 .Lsc_G_gom0
	s_mov_b32 s69, 0x100000

.Lsc_G_gom0:
	ds_write_b32 v159, v161 offset:0
	ds_write_b128 v8, v[72:75] offset:0
	ds_write_b128 v8, v[76:79] offset:128
	ds_write_b128 v8, v[80:83] offset:256
	ds_write_b128 v8, v[84:87] offset:384
	ds_write2_b32 v138, v96, v97 offset0:1 offset1:3
	ds_write2_b32 v139, v88, v89 offset0:0 offset1:2
	ds_write2_b32 v138, v98, v99 offset0:65 offset1:67
	ds_write2_b32 v139, v90, v91 offset0:64 offset1:66
	ds_write2_b32 v138, v100, v101 offset0:33 offset1:35
	ds_write2_b32 v139, v92, v93 offset0:32 offset1:34
	ds_write2_b32 v138, v102, v103 offset0:97 offset1:99
	ds_write2_b32 v139, v94, v95 offset0:96 offset1:98
	ds_write2_b32 v142, v104, v105 offset1:36
	s_cmp_lg_u32 s7, 4
	s_cbranch_scc1 .Lsc_nokb3
	s_and_saveexec_b64 s[68:69], s[12:13]
	ds_write_b128 v158, v[88:91] offset:0
	ds_write_b128 v158, v[92:95] offset:128
	s_mov_b64 exec, s[68:69]
.Lsc_nokb3:
	ds_read_b128 v[106:109], v2 offset:0
	ds_read_b128 v[122:125], v2 offset:16384
	ds_read_b128 v[110:113], v3 offset:0
	ds_read_b128 v[126:129], v3 offset:16384
	ds_read_b128 v[114:117], v4 offset:0
	ds_read_b128 v[130:133], v4 offset:16384
	ds_read_b128 v[118:121], v10 offset:0
	ds_read_b128 v[134:137], v10 offset:16384
	s_waitcnt lgkmcnt(0)
	v_pk_add_f32 v[106:107], v[106:107], v[108:109]
	v_pk_add_f32 v[110:111], v[110:111], v[112:113]
	v_pk_add_f32 v[114:115], v[114:115], v[116:117]
	v_pk_add_f32 v[118:119], v[118:119], v[120:121]
	v_pk_add_f32 v[106:107], v[106:107], v[110:111]
	v_pk_add_f32 v[114:115], v[114:115], v[118:119]
	v_pk_add_f32 v[106:107], v[106:107], v[114:115]
	v_add_f32_e32 v64, v106, v107
	v_pk_add_f32 v[122:123], v[122:123], v[124:125]
	v_pk_add_f32 v[126:127], v[126:127], v[128:129]
	v_pk_add_f32 v[130:131], v[130:131], v[132:133]
	v_pk_add_f32 v[134:135], v[134:135], v[136:137]
	v_pk_add_f32 v[122:123], v[122:123], v[126:127]
	v_pk_add_f32 v[130:131], v[130:131], v[134:135]
	v_pk_add_f32 v[122:123], v[122:123], v[130:131]
	v_add_f32_e32 v65, v122, v123
	global_store_dword v7, v64, s[48:49]
	global_store_dword v165, v65, s[48:49]
	v_add_u32_e32 v7, s64, v7
	v_add_u32_e32 v165, s64, v165
	s_add_i32 s6, s6, 1
	v_add_u32_e32 v146, 1, v146
	s_waitcnt lgkmcnt(0)
	ds_write_b32 v145, v146
	s_waitcnt vmcnt(10)
	v_lshlrev_b32_e32 v64, 16, v54
	v_and_b32_e32 v65, 0xffff0000, v54
	v_lshlrev_b32_e32 v66, 16, v55
	v_and_b32_e32 v67, 0xffff0000, v55
	v_lshlrev_b32_e32 v68, 16, v56
	v_and_b32_e32 v69, 0xffff0000, v56
	v_lshlrev_b32_e32 v70, 16, v57
	v_and_b32_e32 v71, 0xffff0000, v57
	ds_write_b128 v153, v[64:67]
	ds_write_b128 v153, v[68:71] offset:128
	s_waitcnt lgkmcnt(0)
	ds_read_b32 v124, v154 offset:0
	ds_read_b32 v125, v154 offset:256
	ds_read_b32 v126, v154 offset:512
	ds_read_b32 v127, v154 offset:768
	ds_read_b32 v128, v154 offset:1024
	ds_read_b32 v129, v154 offset:1280
	ds_read_b32 v130, v154 offset:1536
	ds_read_b32 v131, v154 offset:1792
	v_lshlrev_b32_e32 v108, 16, v50
	v_and_b32_e32 v109, 0xffff0000, v50
	v_lshlrev_b32_e32 v110, 16, v58
	v_and_b32_e32 v111, 0xffff0000, v58
	v_lshlrev_b32_e32 v96, 16, v46
	v_and_b32_e32 v97, 0xffff0000, v46
	v_pk_mul_f32 v[114:115], v[12:13], v[108:109]
	v_pk_fma_f32 v[112:113], v[20:21], v[110:111], v[190:191]
	v_pk_mul_f32 v[88:89], v[62:63], v[114:115] op_sel_hi:[0,1]
	v_pk_mul_f32 v[72:73], v[112:113], v[108:109]
	v_pk_mul_f32 v[80:81], v[88:89], v[110:111]
	v_lshlrev_b32_e32 v108, 16, v51
	v_and_b32_e32 v109, 0xffff0000, v51
	v_lshlrev_b32_e32 v110, 16, v59
	v_and_b32_e32 v111, 0xffff0000, v59
	v_lshlrev_b32_e32 v98, 16, v47
	v_and_b32_e32 v99, 0xffff0000, v47
	v_pk_mul_f32 v[114:115], v[14:15], v[108:109]
	v_pk_fma_f32 v[112:113], v[22:23], v[110:111], v[192:193]
	v_pk_mul_f32 v[90:91], v[62:63], v[114:115] op_sel_hi:[0,1]
	v_pk_mul_f32 v[74:75], v[112:113], v[108:109]
	v_pk_mul_f32 v[82:83], v[90:91], v[110:111]
	v_lshlrev_b32_e32 v108, 16, v52
	v_and_b32_e32 v109, 0xffff0000, v52
	v_lshlrev_b32_e32 v110, 16, v60
	v_and_b32_e32 v111, 0xffff0000, v60
	v_lshlrev_b32_e32 v100, 16, v48
	v_and_b32_e32 v101, 0xffff0000, v48
	v_pk_mul_f32 v[114:115], v[16:17], v[108:109]
	v_pk_fma_f32 v[112:113], v[24:25], v[110:111], v[194:195]
	v_pk_mul_f32 v[92:93], v[62:63], v[114:115] op_sel_hi:[0,1]
	v_pk_mul_f32 v[76:77], v[112:113], v[108:109]
	v_pk_mul_f32 v[84:85], v[92:93], v[110:111]
	v_lshlrev_b32_e32 v108, 16, v53
	v_and_b32_e32 v109, 0xffff0000, v53
	v_lshlrev_b32_e32 v110, 16, v61
	v_and_b32_e32 v111, 0xffff0000, v61
	v_lshlrev_b32_e32 v102, 16, v49
	v_and_b32_e32 v103, 0xffff0000, v49
	v_pk_mul_f32 v[114:115], v[18:19], v[108:109]
	v_pk_fma_f32 v[112:113], v[26:27], v[110:111], v[196:197]
	v_pk_mul_f32 v[94:95], v[62:63], v[114:115] op_sel_hi:[0,1]
	v_pk_mul_f32 v[78:79], v[112:113], v[108:109]
	v_pk_mul_f32 v[86:87], v[94:95], v[110:111]
	v_lshlrev_b32_e32 v104, 16, v63
	v_and_b32_e32 v105, 0xffff0000, v63
	s_waitcnt lgkmcnt(0)
	v_add_f32_e32 v125, v124, v125
	v_add_f32_e32 v126, v125, v126
	v_add_f32_e32 v127, v126, v127
	v_add_f32_e32 v128, v127, v128
	v_add_f32_e32 v129, v128, v129
	v_add_f32_e32 v130, v129, v130
	v_add_f32_e32 v131, v130, v131
	s_and_b32 s72, s6, 3
	s_lshl_b32 s72, s72, 10
	v_add_u32_e32 v182, s72, v180
	v_add_u32_e32 v183, s72, v181
	v_mul_f32_e32 v189, 0x3fb8aa3b, v131
	ds_write_b32 v182, v189
	v_add_u32_e32 v184, 1, v146
	s_waitcnt lgkmcnt(0)
	ds_write_b32 v162, v184
	s_add_u32 s73, s6, 1
	s_mov_b32 s69, 0x100000

.Lsc_gf_go4:
	ds_read_b32 v185, v183
	ds_read_b32 v186, v183 offset:256
	ds_read_b32 v187, v183 offset:512
	s_waitcnt lgkmcnt(0)
	v_and_b32_e32 v185, v174, v185
	v_and_b32_e32 v186, v175, v186
	v_and_b32_e32 v187, v176, v187
	v_add_f32_e32 v185, v185, v186
	v_add_f32_e32 v185, v185, v187
	v_fma_f32 v124, v124, s14, v185
	v_fma_f32 v125, v125, s14, v185
	v_fma_f32 v126, v126, s14, v185
	v_fma_f32 v127, v127, s14, v185
	v_fma_f32 v128, v128, s14, v185
	v_fma_f32 v129, v129, s14, v185
	v_fma_f32 v130, v130, s14, v185
	v_fma_f32 v131, v131, s14, v185
	v_exp_f32_e64 v188, -v185
	v_exp_f32_e64 v124, -v124
	v_exp_f32_e64 v125, -v125
	v_exp_f32_e64 v126, -v126
	v_exp_f32_e64 v127, -v127
	v_exp_f32_e64 v128, -v128
	v_exp_f32_e64 v129, -v129
	v_exp_f32_e64 v130, -v130
	v_exp_f32_e64 v131, -v131
	s_nop 0
	ds_write_b32 v155, v188
	ds_write_b32 v155, v124 offset:256
	ds_write_b32 v155, v125 offset:512
	ds_write_b32 v155, v126 offset:768
	ds_write_b32 v155, v127 offset:1024
	ds_write_b32 v155, v128 offset:1280
	ds_write_b32 v155, v129 offset:1536
	ds_write_b32 v155, v130 offset:1792
	ds_write_b32 v155, v131 offset:2048
	v_mov_b32_e32 v161, v131
	s_waitcnt lgkmcnt(0)
	ds_read_b128 v[64:67], v153 offset:2048
	ds_read_b128 v[68:71], v153 offset:2176
	ds_read_b128 v[116:119], v153 offset:2304
	ds_read_b128 v[120:123], v153 offset:2432
	s_waitcnt lgkmcnt(0)
	v_rcp_f32_e32 v124, v116
	v_rcp_f32_e32 v125, v117
	v_rcp_f32_e32 v126, v118
	v_rcp_f32_e32 v127, v119
	v_rcp_f32_e32 v128, v120
	v_rcp_f32_e32 v129, v121
	v_rcp_f32_e32 v130, v122
	v_rcp_f32_e32 v131, v123
	s_nop 1
	v_pk_mul_f32 v[72:73], v[72:73], v[124:125]
	v_pk_mul_f32 v[80:81], v[80:81], v[124:125]
	v_pk_mul_f32 v[88:89], v[88:89], v[64:65]
	v_pk_mul_f32 v[96:97], v[96:97], v[116:117]
	v_pk_mul_f32 v[74:75], v[74:75], v[126:127]
	v_pk_mul_f32 v[82:83], v[82:83], v[126:127]
	v_pk_mul_f32 v[90:91], v[90:91], v[66:67]
	v_pk_mul_f32 v[98:99], v[98:99], v[118:119]
	v_pk_mul_f32 v[76:77], v[76:77], v[128:129]
	v_pk_mul_f32 v[84:85], v[84:85], v[128:129]
	v_pk_mul_f32 v[92:93], v[92:93], v[68:69]
	v_pk_mul_f32 v[100:101], v[100:101], v[120:121]
	v_pk_mul_f32 v[78:79], v[78:79], v[130:131]
	v_pk_mul_f32 v[86:87], v[86:87], v[130:131]
	v_pk_mul_f32 v[94:95], v[94:95], v[70:71]
	v_pk_mul_f32 v[102:103], v[102:103], v[122:123]
	global_load_dwordx2 v[46:47], v5, s[36:37]
	global_load_dwordx2 v[48:49], v5, s[36:37] offset:64
	global_load_dwordx2 v[50:51], v5, s[38:39]
	global_load_dwordx2 v[52:53], v5, s[38:39] offset:64
	global_load_dwordx2 v[54:55], v5, s[40:41]
	global_load_dwordx2 v[56:57], v5, s[40:41] offset:64
	global_load_dwordx2 v[58:59], v5, s[42:43]
	global_load_dwordx2 v[60:61], v5, s[42:43] offset:64
	global_load_dword v62, v6, s[46:47]
	global_load_dword v63, v9, s[44:45]
	v_add_u32_e32 v5, s54, v5
	v_add_u32_e32 v6, s55, v6
	v_add_u32_e32 v9, s54, v9
	s_sub_u32 s65, s6, 1
	ds_read_b128 v[148:151], v144
	s_waitcnt lgkmcnt(0)
	v_min_u32_e32 v148, v148, v149
	v_min3_u32 v148, v148, v150, v151
	s_nop 1
	v_readfirstlane_b32 s68, v148
	s_cmp_ge_u32 s68, s65
	s_cbranch_scc1 .Lsc_G_gom1
	s_mov_b32 s69, 0x100000

.Lsc_G_gom1:
	ds_write_b32 v159, v161 offset:34816
	ds_write_b128 v8, v[72:75] offset:34816
	ds_write_b128 v8, v[76:79] offset:34944
	ds_write_b128 v8, v[80:83] offset:35072
	ds_write_b128 v8, v[84:87] offset:35200
	ds_write2_b32 v140, v96, v97 offset0:1 offset1:3
	ds_write2_b32 v141, v88, v89 offset0:0 offset1:2
	ds_write2_b32 v140, v98, v99 offset0:65 offset1:67
	ds_write2_b32 v141, v90, v91 offset0:64 offset1:66
	ds_write2_b32 v140, v100, v101 offset0:33 offset1:35
	ds_write2_b32 v141, v92, v93 offset0:32 offset1:34
	ds_write2_b32 v140, v102, v103 offset0:97 offset1:99
	ds_write2_b32 v141, v94, v95 offset0:96 offset1:98
	ds_write2_b32 v143, v104, v105 offset1:36
	s_cmp_lg_u32 s7, 4
	s_cbranch_scc1 .Lsc_nokb4
	s_and_saveexec_b64 s[68:69], s[12:13]
	ds_write_b128 v158, v[88:91] offset:34816
	ds_write_b128 v158, v[92:95] offset:34944
	s_mov_b64 exec, s[68:69]
.Lsc_nokb4:
	ds_read_b128 v[106:109], v2 offset:32768
	ds_read_b128 v[122:125], v2 offset:49152
	ds_read_b128 v[110:113], v3 offset:32768
	ds_read_b128 v[126:129], v3 offset:49152
	ds_read_b128 v[114:117], v4 offset:32768
	ds_read_b128 v[130:133], v4 offset:49152
	ds_read_b128 v[118:121], v10 offset:32768
	ds_read_b128 v[134:137], v10 offset:49152
	s_waitcnt lgkmcnt(0)
	v_pk_add_f32 v[106:107], v[106:107], v[108:109]
	v_pk_add_f32 v[110:111], v[110:111], v[112:113]
	v_pk_add_f32 v[114:115], v[114:115], v[116:117]
	v_pk_add_f32 v[118:119], v[118:119], v[120:121]
	v_pk_add_f32 v[106:107], v[106:107], v[110:111]
	v_pk_add_f32 v[114:115], v[114:115], v[118:119]
	v_pk_add_f32 v[106:107], v[106:107], v[114:115]
	v_add_f32_e32 v64, v106, v107
	v_pk_add_f32 v[122:123], v[122:123], v[124:125]
	v_pk_add_f32 v[126:127], v[126:127], v[128:129]
	v_pk_add_f32 v[130:131], v[130:131], v[132:133]
	v_pk_add_f32 v[134:135], v[134:135], v[136:137]
	v_pk_add_f32 v[122:123], v[122:123], v[126:127]
	v_pk_add_f32 v[130:131], v[130:131], v[134:135]
	v_pk_add_f32 v[122:123], v[122:123], v[130:131]
	v_add_f32_e32 v65, v122, v123
	global_store_dword v7, v64, s[48:49]
	global_store_dword v165, v65, s[48:49]
	v_add_u32_e32 v7, s64, v7
	v_add_u32_e32 v165, s64, v165
	s_add_i32 s6, s6, 1
	v_add_u32_e32 v146, 1, v146
	s_waitcnt lgkmcnt(0)
	ds_write_b32 v145, v146
	s_cmp_lt_u32 s6, 0xfe
	s_cbranch_scc1 .Lsc_G_loop
	s_waitcnt vmcnt(10)
	v_lshlrev_b32_e32 v64, 16, v36
	v_and_b32_e32 v65, 0xffff0000, v36
	v_lshlrev_b32_e32 v66, 16, v37
	v_and_b32_e32 v67, 0xffff0000, v37
	v_lshlrev_b32_e32 v68, 16, v38
	v_and_b32_e32 v69, 0xffff0000, v38
	v_lshlrev_b32_e32 v70, 16, v39
	v_and_b32_e32 v71, 0xffff0000, v39
	ds_write_b128 v153, v[64:67]
	ds_write_b128 v153, v[68:71] offset:128
	s_waitcnt lgkmcnt(0)
	ds_read_b32 v124, v154 offset:0
	ds_read_b32 v125, v154 offset:256
	ds_read_b32 v126, v154 offset:512
	ds_read_b32 v127, v154 offset:768
	ds_read_b32 v128, v154 offset:1024
	ds_read_b32 v129, v154 offset:1280
	ds_read_b32 v130, v154 offset:1536
	ds_read_b32 v131, v154 offset:1792
	v_lshlrev_b32_e32 v108, 16, v32
	v_and_b32_e32 v109, 0xffff0000, v32
	v_lshlrev_b32_e32 v110, 16, v40
	v_and_b32_e32 v111, 0xffff0000, v40
	v_lshlrev_b32_e32 v96, 16, v28
	v_and_b32_e32 v97, 0xffff0000, v28
	v_pk_mul_f32 v[114:115], v[12:13], v[108:109]
	v_pk_fma_f32 v[112:113], v[20:21], v[110:111], v[190:191]
	v_pk_mul_f32 v[88:89], v[44:45], v[114:115] op_sel_hi:[0,1]
	v_pk_mul_f32 v[72:73], v[112:113], v[108:109]
	v_pk_mul_f32 v[80:81], v[88:89], v[110:111]
	v_lshlrev_b32_e32 v108, 16, v33
	v_and_b32_e32 v109, 0xffff0000, v33
	v_lshlrev_b32_e32 v110, 16, v41
	v_and_b32_e32 v111, 0xffff0000, v41
	v_lshlrev_b32_e32 v98, 16, v29
	v_and_b32_e32 v99, 0xffff0000, v29
	v_pk_mul_f32 v[114:115], v[14:15], v[108:109]
	v_pk_fma_f32 v[112:113], v[22:23], v[110:111], v[192:193]
	v_pk_mul_f32 v[90:91], v[44:45], v[114:115] op_sel_hi:[0,1]
	v_pk_mul_f32 v[74:75], v[112:113], v[108:109]
	v_pk_mul_f32 v[82:83], v[90:91], v[110:111]
	v_lshlrev_b32_e32 v108, 16, v34
	v_and_b32_e32 v109, 0xffff0000, v34
	v_lshlrev_b32_e32 v110, 16, v42
	v_and_b32_e32 v111, 0xffff0000, v42
	v_lshlrev_b32_e32 v100, 16, v30
	v_and_b32_e32 v101, 0xffff0000, v30
	v_pk_mul_f32 v[114:115], v[16:17], v[108:109]
	v_pk_fma_f32 v[112:113], v[24:25], v[110:111], v[194:195]
	v_pk_mul_f32 v[92:93], v[44:45], v[114:115] op_sel_hi:[0,1]
	v_pk_mul_f32 v[76:77], v[112:113], v[108:109]
	v_pk_mul_f32 v[84:85], v[92:93], v[110:111]
	v_lshlrev_b32_e32 v108, 16, v35
	v_and_b32_e32 v109, 0xffff0000, v35
	v_lshlrev_b32_e32 v110, 16, v43
	v_and_b32_e32 v111, 0xffff0000, v43
	v_lshlrev_b32_e32 v102, 16, v31
	v_and_b32_e32 v103, 0xffff0000, v31
	v_pk_mul_f32 v[114:115], v[18:19], v[108:109]
	v_pk_fma_f32 v[112:113], v[26:27], v[110:111], v[196:197]
	v_pk_mul_f32 v[94:95], v[44:45], v[114:115] op_sel_hi:[0,1]
	v_pk_mul_f32 v[78:79], v[112:113], v[108:109]
	v_pk_mul_f32 v[86:87], v[94:95], v[110:111]
	v_lshlrev_b32_e32 v104, 16, v45
	v_and_b32_e32 v105, 0xffff0000, v45
	s_waitcnt lgkmcnt(0)
	v_add_f32_e32 v125, v124, v125
	v_add_f32_e32 v126, v125, v126
	v_add_f32_e32 v127, v126, v127
	v_add_f32_e32 v128, v127, v128
	v_add_f32_e32 v129, v128, v129
	v_add_f32_e32 v130, v129, v130
	v_add_f32_e32 v131, v130, v131
	s_and_b32 s72, s6, 3
	s_lshl_b32 s72, s72, 10
	v_add_u32_e32 v182, s72, v180
	v_add_u32_e32 v183, s72, v181
	v_mul_f32_e32 v189, 0x3fb8aa3b, v131
	ds_write_b32 v182, v189
	v_add_u32_e32 v184, 1, v146
	s_waitcnt lgkmcnt(0)
	ds_write_b32 v162, v184
	s_add_u32 s73, s6, 1
	s_mov_b32 s69, 0x100000

.Lsc_gf_go5:
	ds_read_b32 v185, v183
	ds_read_b32 v186, v183 offset:256
	ds_read_b32 v187, v183 offset:512
	s_waitcnt lgkmcnt(0)
	v_and_b32_e32 v185, v174, v185
	v_and_b32_e32 v186, v175, v186
	v_and_b32_e32 v187, v176, v187
	v_add_f32_e32 v185, v185, v186
	v_add_f32_e32 v185, v185, v187
	v_fma_f32 v124, v124, s14, v185
	v_fma_f32 v125, v125, s14, v185
	v_fma_f32 v126, v126, s14, v185
	v_fma_f32 v127, v127, s14, v185
	v_fma_f32 v128, v128, s14, v185
	v_fma_f32 v129, v129, s14, v185
	v_fma_f32 v130, v130, s14, v185
	v_fma_f32 v131, v131, s14, v185
	v_exp_f32_e64 v188, -v185
	v_exp_f32_e64 v124, -v124
	v_exp_f32_e64 v125, -v125
	v_exp_f32_e64 v126, -v126
	v_exp_f32_e64 v127, -v127
	v_exp_f32_e64 v128, -v128
	v_exp_f32_e64 v129, -v129
	v_exp_f32_e64 v130, -v130
	v_exp_f32_e64 v131, -v131
	s_nop 0
	ds_write_b32 v155, v188
	ds_write_b32 v155, v124 offset:256
	ds_write_b32 v155, v125 offset:512
	ds_write_b32 v155, v126 offset:768
	ds_write_b32 v155, v127 offset:1024
	ds_write_b32 v155, v128 offset:1280
	ds_write_b32 v155, v129 offset:1536
	ds_write_b32 v155, v130 offset:1792
	ds_write_b32 v155, v131 offset:2048
	v_mov_b32_e32 v161, v131
	s_waitcnt lgkmcnt(0)
	ds_read_b128 v[64:67], v153 offset:2048
	ds_read_b128 v[68:71], v153 offset:2176
	ds_read_b128 v[116:119], v153 offset:2304
	ds_read_b128 v[120:123], v153 offset:2432
	s_waitcnt lgkmcnt(0)
	v_rcp_f32_e32 v124, v116
	v_rcp_f32_e32 v125, v117
	v_rcp_f32_e32 v126, v118
	v_rcp_f32_e32 v127, v119
	v_rcp_f32_e32 v128, v120
	v_rcp_f32_e32 v129, v121
	v_rcp_f32_e32 v130, v122
	v_rcp_f32_e32 v131, v123
	s_nop 1
	v_pk_mul_f32 v[72:73], v[72:73], v[124:125]
	v_pk_mul_f32 v[80:81], v[80:81], v[124:125]
	v_pk_mul_f32 v[88:89], v[88:89], v[64:65]
	v_pk_mul_f32 v[96:97], v[96:97], v[116:117]
	v_pk_mul_f32 v[74:75], v[74:75], v[126:127]
	v_pk_mul_f32 v[82:83], v[82:83], v[126:127]
	v_pk_mul_f32 v[90:91], v[90:91], v[66:67]
	v_pk_mul_f32 v[98:99], v[98:99], v[118:119]
	v_pk_mul_f32 v[76:77], v[76:77], v[128:129]
	v_pk_mul_f32 v[84:85], v[84:85], v[128:129]
	v_pk_mul_f32 v[92:93], v[92:93], v[68:69]
	v_pk_mul_f32 v[100:101], v[100:101], v[120:121]
	v_pk_mul_f32 v[78:79], v[78:79], v[130:131]
	v_pk_mul_f32 v[86:87], v[86:87], v[130:131]
	v_pk_mul_f32 v[94:95], v[94:95], v[70:71]
	v_pk_mul_f32 v[102:103], v[102:103], v[122:123]
	s_sub_u32 s65, s6, 1
	ds_read_b128 v[148:151], v144
	s_waitcnt lgkmcnt(0)
	v_min_u32_e32 v148, v148, v149
	v_min3_u32 v148, v148, v150, v151
	s_nop 1
	v_readfirstlane_b32 s68, v148
	s_cmp_ge_u32 s68, s65
	s_cbranch_scc1 .Lsc_G_goz0
	s_mov_b32 s69, 0x100000

.Lsc_nokb5:
	ds_read_b128 v[106:109], v2 offset:0
	ds_read_b128 v[122:125], v2 offset:16384
	ds_read_b128 v[110:113], v3 offset:0
	ds_read_b128 v[126:129], v3 offset:16384
	ds_read_b128 v[114:117], v4 offset:0
	ds_read_b128 v[130:133], v4 offset:16384
	ds_read_b128 v[118:121], v10 offset:0
	ds_read_b128 v[134:137], v10 offset:16384
	s_waitcnt lgkmcnt(0)
	v_pk_add_f32 v[106:107], v[106:107], v[108:109]
	v_pk_add_f32 v[110:111], v[110:111], v[112:113]
	v_pk_add_f32 v[114:115], v[114:115], v[116:117]
	v_pk_add_f32 v[118:119], v[118:119], v[120:121]
	v_pk_add_f32 v[106:107], v[106:107], v[110:111]
	v_pk_add_f32 v[114:115], v[114:115], v[118:119]
	v_pk_add_f32 v[106:107], v[106:107], v[114:115]
	v_add_f32_e32 v64, v106, v107
	v_pk_add_f32 v[122:123], v[122:123], v[124:125]
	v_pk_add_f32 v[126:127], v[126:127], v[128:129]
	v_pk_add_f32 v[130:131], v[130:131], v[132:133]
	v_pk_add_f32 v[134:135], v[134:135], v[136:137]
	v_pk_add_f32 v[122:123], v[122:123], v[126:127]
	v_pk_add_f32 v[130:131], v[130:131], v[134:135]
	v_pk_add_f32 v[122:123], v[122:123], v[130:131]
	v_add_f32_e32 v65, v122, v123
	global_store_dword v7, v64, s[48:49]
	global_store_dword v165, v65, s[48:49]
	v_add_u32_e32 v7, s64, v7
	v_add_u32_e32 v165, s64, v165
	s_add_i32 s6, s6, 1
	v_add_u32_e32 v146, 1, v146
	s_waitcnt lgkmcnt(0)
	ds_write_b32 v145, v146
	s_waitcnt vmcnt(0)
	v_lshlrev_b32_e32 v64, 16, v54
	v_and_b32_e32 v65, 0xffff0000, v54
	v_lshlrev_b32_e32 v66, 16, v55
	v_and_b32_e32 v67, 0xffff0000, v55
	v_lshlrev_b32_e32 v68, 16, v56
	v_and_b32_e32 v69, 0xffff0000, v56
	v_lshlrev_b32_e32 v70, 16, v57
	v_and_b32_e32 v71, 0xffff0000, v57
	ds_write_b128 v153, v[64:67]
	ds_write_b128 v153, v[68:71] offset:128
	s_waitcnt lgkmcnt(0)
	ds_read_b32 v124, v154 offset:0
	ds_read_b32 v125, v154 offset:256
	ds_read_b32 v126, v154 offset:512
	ds_read_b32 v127, v154 offset:768
	ds_read_b32 v128, v154 offset:1024
	ds_read_b32 v129, v154 offset:1280
	ds_read_b32 v130, v154 offset:1536
	ds_read_b32 v131, v154 offset:1792
	v_lshlrev_b32_e32 v108, 16, v50
	v_and_b32_e32 v109, 0xffff0000, v50
	v_lshlrev_b32_e32 v110, 16, v58
	v_and_b32_e32 v111, 0xffff0000, v58
	v_lshlrev_b32_e32 v96, 16, v46
	v_and_b32_e32 v97, 0xffff0000, v46
	v_pk_mul_f32 v[114:115], v[12:13], v[108:109]
	v_pk_fma_f32 v[112:113], v[20:21], v[110:111], v[190:191]
	v_pk_mul_f32 v[88:89], v[62:63], v[114:115] op_sel_hi:[0,1]
	v_pk_mul_f32 v[72:73], v[112:113], v[108:109]
	v_pk_mul_f32 v[80:81], v[88:89], v[110:111]
	v_lshlrev_b32_e32 v108, 16, v51
	v_and_b32_e32 v109, 0xffff0000, v51
	v_lshlrev_b32_e32 v110, 16, v59
	v_and_b32_e32 v111, 0xffff0000, v59
	v_lshlrev_b32_e32 v98, 16, v47
	v_and_b32_e32 v99, 0xffff0000, v47
	v_pk_mul_f32 v[114:115], v[14:15], v[108:109]
	v_pk_fma_f32 v[112:113], v[22:23], v[110:111], v[192:193]
	v_pk_mul_f32 v[90:91], v[62:63], v[114:115] op_sel_hi:[0,1]
	v_pk_mul_f32 v[74:75], v[112:113], v[108:109]
	v_pk_mul_f32 v[82:83], v[90:91], v[110:111]
	v_lshlrev_b32_e32 v108, 16, v52
	v_and_b32_e32 v109, 0xffff0000, v52
	v_lshlrev_b32_e32 v110, 16, v60
	v_and_b32_e32 v111, 0xffff0000, v60
	v_lshlrev_b32_e32 v100, 16, v48
	v_and_b32_e32 v101, 0xffff0000, v48
	v_pk_mul_f32 v[114:115], v[16:17], v[108:109]
	v_pk_fma_f32 v[112:113], v[24:25], v[110:111], v[194:195]
	v_pk_mul_f32 v[92:93], v[62:63], v[114:115] op_sel_hi:[0,1]
	v_pk_mul_f32 v[76:77], v[112:113], v[108:109]
	v_pk_mul_f32 v[84:85], v[92:93], v[110:111]
	v_lshlrev_b32_e32 v108, 16, v53
	v_and_b32_e32 v109, 0xffff0000, v53
	v_lshlrev_b32_e32 v110, 16, v61
	v_and_b32_e32 v111, 0xffff0000, v61
	v_lshlrev_b32_e32 v102, 16, v49
	v_and_b32_e32 v103, 0xffff0000, v49
	v_pk_mul_f32 v[114:115], v[18:19], v[108:109]
	v_pk_fma_f32 v[112:113], v[26:27], v[110:111], v[196:197]
	v_pk_mul_f32 v[94:95], v[62:63], v[114:115] op_sel_hi:[0,1]
	v_pk_mul_f32 v[78:79], v[112:113], v[108:109]
	v_pk_mul_f32 v[86:87], v[94:95], v[110:111]
	v_lshlrev_b32_e32 v104, 16, v63
	v_and_b32_e32 v105, 0xffff0000, v63
	s_waitcnt lgkmcnt(0)
	v_add_f32_e32 v125, v124, v125
	v_add_f32_e32 v126, v125, v126
	v_add_f32_e32 v127, v126, v127
	v_add_f32_e32 v128, v127, v128
	v_add_f32_e32 v129, v128, v129
	v_add_f32_e32 v130, v129, v130
	v_add_f32_e32 v131, v130, v131
	s_and_b32 s72, s6, 3
	s_lshl_b32 s72, s72, 10
	v_add_u32_e32 v182, s72, v180
	v_add_u32_e32 v183, s72, v181
	v_mul_f32_e32 v189, 0x3fb8aa3b, v131
	ds_write_b32 v182, v189
	v_add_u32_e32 v184, 1, v146
	s_waitcnt lgkmcnt(0)
	ds_write_b32 v162, v184
	s_add_u32 s73, s6, 1
	s_mov_b32 s69, 0x100000

.Lsc_nokb6:
	ds_read_b128 v[106:109], v2 offset:32768
	ds_read_b128 v[122:125], v2 offset:49152
	ds_read_b128 v[110:113], v3 offset:32768
	ds_read_b128 v[126:129], v3 offset:49152
	ds_read_b128 v[114:117], v4 offset:32768
	ds_read_b128 v[130:133], v4 offset:49152
	ds_read_b128 v[118:121], v10 offset:32768
	ds_read_b128 v[134:137], v10 offset:49152
	s_waitcnt lgkmcnt(0)
	v_pk_add_f32 v[106:107], v[106:107], v[108:109]
	v_pk_add_f32 v[110:111], v[110:111], v[112:113]
	v_pk_add_f32 v[114:115], v[114:115], v[116:117]
	v_pk_add_f32 v[118:119], v[118:119], v[120:121]
	v_pk_add_f32 v[106:107], v[106:107], v[110:111]
	v_pk_add_f32 v[114:115], v[114:115], v[118:119]
	v_pk_add_f32 v[106:107], v[106:107], v[114:115]
	v_add_f32_e32 v64, v106, v107
	v_pk_add_f32 v[122:123], v[122:123], v[124:125]
	v_pk_add_f32 v[126:127], v[126:127], v[128:129]
	v_pk_add_f32 v[130:131], v[130:131], v[132:133]
	v_pk_add_f32 v[134:135], v[134:135], v[136:137]
	v_pk_add_f32 v[122:123], v[122:123], v[126:127]
	v_pk_add_f32 v[130:131], v[130:131], v[134:135]
	v_pk_add_f32 v[122:123], v[122:123], v[130:131]
	v_add_f32_e32 v65, v122, v123
	global_store_dword v7, v64, s[48:49]
	global_store_dword v165, v65, s[48:49]
	v_add_u32_e32 v7, s64, v7
	v_add_u32_e32 v165, s64, v165
	s_add_i32 s6, s6, 1
	v_add_u32_e32 v146, 1, v146
	s_waitcnt lgkmcnt(0)
	ds_write_b32 v145, v146
	s_sub_u32 s65, s6, 1
	ds_read_b128 v[148:151], v144
	s_waitcnt lgkmcnt(0)
	v_min_u32_e32 v148, v148, v149
	v_min3_u32 v148, v148, v150, v151
	s_nop 1
	v_readfirstlane_b32 s68, v148
	s_cmp_ge_u32 s68, s65
	s_cbranch_scc1 .Lsc_G_goz2
	s_mov_b32 s69, 0x100000
